# cmp finalize: issue the 8 split-K partial loads and the 32 w2 loads of the hid.w2 dot together (counted waits), same f32 summation order
# speedup vs baseline: 1.0149x; 1.0149x over previous
; DI bf16_t f2bf(float f) { return (bf16_t)(cvtpk(f, 0.f) & 0xffffu); }
; DI float silu(float x) { return x * __builtin_amdgcn_rcpf(1.f + __expf(-x)); }
; __global__ void __launch_bounds__(NTHR) fwd_megakernel(Params p) {
;     ...
;       for (int row = bid; row < 2048; row += nblk) {
;         const int kv = row >> 10, rr = row & 1023, b = rr >> 9, n = (rr & 511) >> 1, g = rr & 1;
;         __syncthreads();
;         if (tid < 128) { float s = 0; for (int k = 0; k < 8; ++k) s += cpart[((size_t)k * 2048 + row) * 256 + kv * 128 + tid]; hid[tid] = silu(s); }
;         __syncthreads();
;         { const int cp = tid & 127, part = tid >> 7; const float* w2 = p.cmp_w2 + (size_t)(l * 2 + kv) * 128 * 128;
;           float s = 0; for (int c = part * 32; c < part * 32 + 32; ++c) s += hid[c] * w2[c * 128 + cp];
;           red[part * 128 + cp] = s; }
;         __syncthreads();
;         if (tid < 128) { const float s = red[tid] + red[128 + tid] + red[256 + tid] + red[384 + tid];
;           if (kv == 0) kc_[(size_t)((b * 2 + g) * 256 + n) * 128 + tid] = f2bf(s); else vct[(size_t)((b * 2 + g) * 128 + tid) * 256 + n] = f2bf(s); }
.LBB0_1097:
	s_ashr_i32 s6, s2, 10
	s_barrier
	s_and_saveexec_b64 s[4:5], s[0:1]
	s_cbranch_execz .LBB0_1099
	s_lshl_b32 s8, s6, 7
	s_ashr_i32 s3, s2, 31
	s_ashr_i32 s9, s8, 31
	v_lshl_add_u64 v[8:9], s[8:9], 2, v[4:5]
	s_lshl_b64 s[8:9], s[2:3], 10
	v_lshl_add_u64 v[8:9], v[8:9], 0, s[8:9]
	global_load_dword v13, v[8:9], off
	s_mov_b64 s[10:11], 0x200000
	v_lshl_add_u64 v[14:15], v[8:9], 0, s[10:11]
	global_load_dword v20, v[14:15], off
	s_mov_b64 s[10:11], 0x400000
	v_lshl_add_u64 v[14:15], v[8:9], 0, s[10:11]
	global_load_dword v21, v[14:15], off
	s_mov_b64 s[10:11], 0x600000
	v_lshl_add_u64 v[14:15], v[8:9], 0, s[10:11]
	global_load_dword v22, v[14:15], off
	s_mov_b64 s[10:11], 0x800000
	v_lshl_add_u64 v[14:15], v[8:9], 0, s[10:11]
	global_load_dword v23, v[14:15], off
	s_mov_b64 s[10:11], 0xa00000
	v_lshl_add_u64 v[14:15], v[8:9], 0, s[10:11]
	global_load_dword v24, v[14:15], off
	s_mov_b64 s[10:11], 0xc00000
	v_lshl_add_u64 v[14:15], v[8:9], 0, s[10:11]
	global_load_dword v25, v[14:15], off
	s_mov_b64 s[10:11], 0xe00000
	v_lshl_add_u64 v[14:15], v[8:9], 0, s[10:11]
	global_load_dword v26, v[14:15], off
	s_waitcnt vmcnt(7)
	v_add_f32_e32 v13, 0, v13
	s_waitcnt vmcnt(6)
	v_add_f32_e32 v13, v13, v20
	s_waitcnt vmcnt(5)
	v_add_f32_e32 v13, v13, v21
	s_waitcnt vmcnt(4)
	v_add_f32_e32 v13, v13, v22
	s_waitcnt vmcnt(3)
	v_add_f32_e32 v13, v13, v23
	s_waitcnt vmcnt(2)
	v_add_f32_e32 v13, v13, v24
	s_waitcnt vmcnt(1)
	v_add_f32_e32 v13, v13, v25
	s_waitcnt vmcnt(0)
	v_add_f32_e32 v8, v13, v26
	v_mul_f32_e32 v9, 0xbfb8aa3b, v8
	v_exp_f32_e32 v9, v9
	s_nop 0
	v_add_f32_e32 v9, 1.0, v9
	v_rcp_f32_e32 v9, v9
	s_nop 0
	v_mul_f32_e32 v8, v8, v9
	ds_write_b32 v0, v8
.LBB0_1099:
	s_or_b64 exec, exec, s[4:5]
	v_readlane_b32 s4, v252, 41
	v_readlane_b32 s5, v252, 42
	s_add_i32 s4, s6, s4
	s_ashr_i32 s5, s4, 31
	s_lshl_b64 s[4:5], s[4:5], 16
	v_readlane_b32 s8, v249, 0
	v_readlane_b32 s9, v249, 1
	s_add_u32 s4, s8, s4
	s_addc_u32 s5, s9, s5
	v_mov_b32_e32 v13, 0
	s_mov_b64 s[6:7], 0
	v_mov_b32_e32 v14, v12
	v_mov_b32_e32 v8, v11
	v_mov_b32_e32 v15, v10
	s_waitcnt lgkmcnt(0)
	s_barrier
	v_readlane_b32 s10, v249, 2
	v_readlane_b32 s11, v249, 3
	v_readlane_b32 s12, v249, 4
	v_readlane_b32 s13, v249, 5
	v_readlane_b32 s14, v249, 6
	v_readlane_b32 s15, v249, 7
	v_readlane_b32 s16, v249, 8
	v_readlane_b32 s17, v249, 9
	v_readlane_b32 s18, v249, 10
	v_readlane_b32 s19, v249, 11
	v_readlane_b32 s20, v249, 12
	v_readlane_b32 s21, v249, 13
	v_readlane_b32 s22, v249, 14
	v_readlane_b32 s23, v249, 15
	v_ashrrev_i32_e32 v9, 31, v8
	v_lshl_add_u64 v[16:17], v[8:9], 2, s[4:5]
	global_load_dword v20, v[16:17], off
	global_load_dword v21, v[16:17], off offset:512
	global_load_dword v22, v[16:17], off offset:1024
	global_load_dword v23, v[16:17], off offset:1536
	global_load_dword v24, v[16:17], off offset:2048
	global_load_dword v25, v[16:17], off offset:2560
	global_load_dword v26, v[16:17], off offset:3072
	global_load_dword v27, v[16:17], off offset:3584
	s_mov_b64 s[6:7], 0x1000
	v_lshl_add_u64 v[16:17], v[16:17], 0, s[6:7]
	global_load_dword v28, v[16:17], off
	global_load_dword v29, v[16:17], off offset:512
	global_load_dword v30, v[16:17], off offset:1024
	global_load_dword v31, v[16:17], off offset:1536
	global_load_dword v32, v[16:17], off offset:2048
	global_load_dword v33, v[16:17], off offset:2560
	global_load_dword v34, v[16:17], off offset:3072
	global_load_dword v35, v[16:17], off offset:3584
	s_mov_b64 s[6:7], 0x1000
	v_lshl_add_u64 v[16:17], v[16:17], 0, s[6:7]
	global_load_dword v36, v[16:17], off
	global_load_dword v37, v[16:17], off offset:512
	global_load_dword v38, v[16:17], off offset:1024
	global_load_dword v39, v[16:17], off offset:1536
	global_load_dword v40, v[16:17], off offset:2048
	global_load_dword v41, v[16:17], off offset:2560
	global_load_dword v42, v[16:17], off offset:3072
	global_load_dword v43, v[16:17], off offset:3584
	s_mov_b64 s[6:7], 0x1000
	v_lshl_add_u64 v[16:17], v[16:17], 0, s[6:7]
	global_load_dword v44, v[16:17], off
	global_load_dword v45, v[16:17], off offset:512
	global_load_dword v46, v[16:17], off offset:1024
	global_load_dword v47, v[16:17], off offset:1536
	global_load_dword v48, v[16:17], off offset:2048
	global_load_dword v49, v[16:17], off offset:2560
	global_load_dword v50, v[16:17], off offset:3072
	global_load_dword v51, v[16:17], off offset:3584
	ds_read_b128 v[52:55], v14
	ds_read_b128 v[56:59], v14 offset:16
	ds_read_b128 v[60:63], v14 offset:32
	ds_read_b128 v[64:67], v14 offset:48
	ds_read_b128 v[68:71], v14 offset:64
	ds_read_b128 v[72:75], v14 offset:80
	ds_read_b128 v[76:79], v14 offset:96
	ds_read_b128 v[80:83], v14 offset:112
	s_waitcnt lgkmcnt(0)
	s_waitcnt vmcnt(24)
	v_fmac_f32_e32 v13, v52, v20
	v_fmac_f32_e32 v13, v53, v21
	v_fmac_f32_e32 v13, v54, v22
	v_fmac_f32_e32 v13, v55, v23
	v_fmac_f32_e32 v13, v56, v24
	v_fmac_f32_e32 v13, v57, v25
	v_fmac_f32_e32 v13, v58, v26
	v_fmac_f32_e32 v13, v59, v27
	s_waitcnt vmcnt(16)
	v_fmac_f32_e32 v13, v60, v28
	v_fmac_f32_e32 v13, v61, v29
	v_fmac_f32_e32 v13, v62, v30
	v_fmac_f32_e32 v13, v63, v31
	v_fmac_f32_e32 v13, v64, v32
	v_fmac_f32_e32 v13, v65, v33
	v_fmac_f32_e32 v13, v66, v34
	v_fmac_f32_e32 v13, v67, v35
	s_waitcnt vmcnt(8)
	v_fmac_f32_e32 v13, v68, v36
	v_fmac_f32_e32 v13, v69, v37
	v_fmac_f32_e32 v13, v70, v38
	v_fmac_f32_e32 v13, v71, v39
	v_fmac_f32_e32 v13, v72, v40
	v_fmac_f32_e32 v13, v73, v41
	v_fmac_f32_e32 v13, v74, v42
	v_fmac_f32_e32 v13, v75, v43
	s_waitcnt vmcnt(0)
	v_fmac_f32_e32 v13, v76, v44
	v_fmac_f32_e32 v13, v77, v45
	v_fmac_f32_e32 v13, v78, v46
	v_fmac_f32_e32 v13, v79, v47
	v_fmac_f32_e32 v13, v80, v48
	v_fmac_f32_e32 v13, v81, v49
	v_fmac_f32_e32 v13, v82, v50
	v_fmac_f32_e32 v13, v83, v51
	ds_write_b32 v0, v13 offset:512
	s_waitcnt lgkmcnt(0)
	s_barrier
	s_and_saveexec_b64 s[4:5], s[0:1]
	s_cbranch_execz .LBB0_1096
	ds_read2st64_b32 v[8:9], v0 offset0:2 offset1:4
	s_bfe_u32 s3, s2, 0x80001
	s_and_b32 s8, s2, 1
	s_mov_b64 s[6:7], -1
	s_cmpk_gt_u32 s2, 0x3ff
	s_waitcnt lgkmcnt(0)
	v_add_f32_e32 v13, v8, v9
	ds_read2st64_b32 v[8:9], v0 offset0:6 offset1:8
	s_waitcnt lgkmcnt(0)
	v_add_f32_e32 v8, v13, v8
	v_add_f32_e32 v8, v8, v9
	s_cbranch_scc0 .LBB0_1104
	s_lshr_b32 s6, s2, 1
	s_and_b32 s6, s6, 0x100
	s_lshl_b32 s7, s8, 7
	s_or_b32 s6, s6, s7
	v_add_u32_e32 v14, s6, v2
	v_ashrrev_i32_e32 v15, 31, v14
	v_readlane_b32 s6, v251, 8
	v_lshlrev_b64 v[14:15], 9, v[14:15]
	v_readlane_b32 s7, v251, 9
	s_lshl_b32 s72, s3, 1
	v_cvt_pk_bf16_f32 v9, v8, v1
	s_nop 0
	v_lshl_add_u64 v[14:15], s[6:7], 0, v[14:15]
	v_lshl_add_u64 v[14:15], v[14:15], 0, s[72:73]
	global_store_short v[14:15], v9, off
	s_mov_b64 s[6:7], 0
